# LRU: hoisted constants + double-buffered uc tile + merged look-back loads (decoupled tile pipeline)
# baseline (speedup 1.0000x reference)
; __device__ __forceinline__ float bf2f(u16 h) { return __uint_as_float(((unsigned)h) << 16); }
; __device__ __forceinline__ void lru_tile(const Params& P, int chunk, int head, int pass, char* smem_raw) {
;     ...
;     const float w0 = P.conv_w[gch], w1 = P.conv_w[512 + gch], w2 = P.conv_w[1024 + gch], w3 = P.conv_w[1536 + gch];
;     const float cb = P.conv_b[gch];
;     const u16* zu = P.zq + gch;
;     const int r = row0 + q * 32;
;     float uv[35];
; #pragma unroll
;     for (int i = 0; i < 35; ++i) {
;       const int rr = r - 2 + i;
;       uv[i] = (rr >= seq_lo && rr < seq_hi) ? bf2f(zu[(long)rr * 1536]) : 0.f;
;     }
;     __syncthreads();
; #pragma unroll
;     for (int i = 0; i < 32; ++i) {
;       const float v = cb + uv[i] * w0 + uv[i + 1] * w1 + uv[i + 2] * w2 + uv[i + 3] * w3;
;       sm_uc[(q * 32 + i) * LDSS + ch] = f2bf(v);
;     }
.Lmy_lrub_fl:
	s_cmp_eq_u32 s57, 0
	s_cselect_b64 s[0:1], s[84:85], 0
	s_cmp_eq_u32 s57, s60
	s_cselect_b64 s[4:5], s[86:87], 0
	v_cndmask_b32_e64 v202, 1.0, 0, s[0:1]
	v_cndmask_b32_e64 v203, 1.0, 0, s[4:5]
	s_waitcnt vmcnt(32)
	v_lshlrev_b32_e32 v90, 16, v32
	v_lshlrev_b32_e32 v91, 16, v33
	v_lshlrev_b32_e32 v92, 16, v34
	v_lshlrev_b32_e32 v93, 16, v35
	v_lshlrev_b32_e32 v94, 16, v36
	v_lshlrev_b32_e32 v95, 16, v37
	v_lshlrev_b32_e32 v96, 16, v38
	v_lshlrev_b32_e32 v97, 16, v39
	v_lshlrev_b32_e32 v98, 16, v40
	v_lshlrev_b32_e32 v99, 16, v41
	v_lshlrev_b32_e32 v100, 16, v42
	v_lshlrev_b32_e32 v101, 16, v43
	v_lshlrev_b32_e32 v102, 16, v44
	v_lshlrev_b32_e32 v103, 16, v45
	v_lshlrev_b32_e32 v104, 16, v46
	v_lshlrev_b32_e32 v105, 16, v47
	v_lshlrev_b32_e32 v106, 16, v48
	v_lshlrev_b32_e32 v107, 16, v49
	v_lshlrev_b32_e32 v108, 16, v50
	v_lshlrev_b32_e32 v109, 16, v51
	v_lshlrev_b32_e32 v110, 16, v52
	v_lshlrev_b32_e32 v111, 16, v53
	v_lshlrev_b32_e32 v112, 16, v54
	v_lshlrev_b32_e32 v113, 16, v55
	v_lshlrev_b32_e32 v114, 16, v56
	v_lshlrev_b32_e32 v115, 16, v57
	v_lshlrev_b32_e32 v116, 16, v58
	v_lshlrev_b32_e32 v117, 16, v59
	v_lshlrev_b32_e32 v118, 16, v60
	v_lshlrev_b32_e32 v119, 16, v61
	v_lshlrev_b32_e32 v120, 16, v62
	v_lshlrev_b32_e32 v121, 16, v63
	v_lshlrev_b32_e32 v122, 16, v64
	v_lshlrev_b32_e32 v123, 16, v66
	v_lshlrev_b32_e32 v124, 16, v69
	v_mul_f32_e32 v90, v90, v202
	v_mul_f32_e32 v91, v91, v202
	v_mul_f32_e32 v124, v124, v203
	v_fma_f32 v162, v90, v65, v73
	v_fma_f32 v162, v91, v67, v162
	v_fma_f32 v162, v92, v68, v162
	v_fma_f32 v162, v93, v70, v162
	v_fma_f32 v163, v91, v65, v73
	v_fma_f32 v163, v92, v67, v163
	v_fma_f32 v163, v93, v68, v163
	v_fma_f32 v163, v94, v70, v163
	v_fma_f32 v164, v92, v65, v73
	v_fma_f32 v164, v93, v67, v164
	v_fma_f32 v164, v94, v68, v164
	v_fma_f32 v164, v95, v70, v164
	v_fma_f32 v165, v93, v65, v73
	v_fma_f32 v165, v94, v67, v165
	v_fma_f32 v165, v95, v68, v165
	v_fma_f32 v165, v96, v70, v165
	v_fma_f32 v166, v94, v65, v73
	v_fma_f32 v166, v95, v67, v166
	v_fma_f32 v166, v96, v68, v166
	v_fma_f32 v166, v97, v70, v166
	v_fma_f32 v167, v95, v65, v73
	v_fma_f32 v167, v96, v67, v167
	v_fma_f32 v167, v97, v68, v167
	v_fma_f32 v167, v98, v70, v167
	v_fma_f32 v168, v96, v65, v73
	v_fma_f32 v168, v97, v67, v168
	v_fma_f32 v168, v98, v68, v168
	v_fma_f32 v168, v99, v70, v168
	v_fma_f32 v169, v97, v65, v73
	v_fma_f32 v169, v98, v67, v169
	v_fma_f32 v169, v99, v68, v169
	v_fma_f32 v169, v100, v70, v169
	v_fma_f32 v170, v98, v65, v73
	v_fma_f32 v170, v99, v67, v170
	v_fma_f32 v170, v100, v68, v170
	v_fma_f32 v170, v101, v70, v170
	v_fma_f32 v171, v99, v65, v73
	v_fma_f32 v171, v100, v67, v171
	v_fma_f32 v171, v101, v68, v171
	v_fma_f32 v171, v102, v70, v171
	v_fma_f32 v172, v100, v65, v73
	v_fma_f32 v172, v101, v67, v172
	v_fma_f32 v172, v102, v68, v172
	v_fma_f32 v172, v103, v70, v172
	v_fma_f32 v173, v101, v65, v73
	v_fma_f32 v173, v102, v67, v173
	v_fma_f32 v173, v103, v68, v173
	v_fma_f32 v173, v104, v70, v173
	v_fma_f32 v174, v102, v65, v73
	v_fma_f32 v174, v103, v67, v174
	v_fma_f32 v174, v104, v68, v174
	v_fma_f32 v174, v105, v70, v174
	v_fma_f32 v175, v103, v65, v73
	v_fma_f32 v175, v104, v67, v175
	v_fma_f32 v175, v105, v68, v175
	v_fma_f32 v175, v106, v70, v175
	v_fma_f32 v176, v104, v65, v73
	v_fma_f32 v176, v105, v67, v176
	v_fma_f32 v176, v106, v68, v176
	v_fma_f32 v176, v107, v70, v176
	v_fma_f32 v177, v105, v65, v73
	v_fma_f32 v177, v106, v67, v177
	v_fma_f32 v177, v107, v68, v177
	v_fma_f32 v177, v108, v70, v177
	v_fma_f32 v178, v106, v65, v73
	v_fma_f32 v178, v107, v67, v178
	v_fma_f32 v178, v108, v68, v178
	v_fma_f32 v178, v109, v70, v178
	v_fma_f32 v179, v107, v65, v73
	v_fma_f32 v179, v108, v67, v179
	v_fma_f32 v179, v109, v68, v179
	v_fma_f32 v179, v110, v70, v179
	v_fma_f32 v180, v108, v65, v73
	v_fma_f32 v180, v109, v67, v180
	v_fma_f32 v180, v110, v68, v180
	v_fma_f32 v180, v111, v70, v180
	v_fma_f32 v181, v109, v65, v73
	v_fma_f32 v181, v110, v67, v181
	v_fma_f32 v181, v111, v68, v181
	v_fma_f32 v181, v112, v70, v181
	v_fma_f32 v182, v110, v65, v73
	v_fma_f32 v182, v111, v67, v182
	v_fma_f32 v182, v112, v68, v182
	v_fma_f32 v182, v113, v70, v182
	v_fma_f32 v183, v111, v65, v73
	v_fma_f32 v183, v112, v67, v183
	v_fma_f32 v183, v113, v68, v183
	v_fma_f32 v183, v114, v70, v183
	v_fma_f32 v184, v112, v65, v73
	v_fma_f32 v184, v113, v67, v184
	v_fma_f32 v184, v114, v68, v184
	v_fma_f32 v184, v115, v70, v184
	v_fma_f32 v185, v113, v65, v73
	v_fma_f32 v185, v114, v67, v185
	v_fma_f32 v185, v115, v68, v185
	v_fma_f32 v185, v116, v70, v185
	v_fma_f32 v186, v114, v65, v73
	v_fma_f32 v186, v115, v67, v186
	v_fma_f32 v186, v116, v68, v186
	v_fma_f32 v186, v117, v70, v186
	v_fma_f32 v187, v115, v65, v73
	v_fma_f32 v187, v116, v67, v187
	v_fma_f32 v187, v117, v68, v187
	v_fma_f32 v187, v118, v70, v187
	v_fma_f32 v188, v116, v65, v73
	v_fma_f32 v188, v117, v67, v188
	v_fma_f32 v188, v118, v68, v188
	v_fma_f32 v188, v119, v70, v188
	v_fma_f32 v189, v117, v65, v73
	v_fma_f32 v189, v118, v67, v189
	v_fma_f32 v189, v119, v68, v189
	v_fma_f32 v189, v120, v70, v189
	v_fma_f32 v190, v118, v65, v73
	v_fma_f32 v190, v119, v67, v190
	v_fma_f32 v190, v120, v68, v190
	v_fma_f32 v190, v121, v70, v190
	v_fma_f32 v191, v119, v65, v73
	v_fma_f32 v191, v120, v67, v191
	v_fma_f32 v191, v121, v68, v191
	v_fma_f32 v191, v122, v70, v191
	v_fma_f32 v192, v120, v65, v73
	v_fma_f32 v192, v121, v67, v192
	v_fma_f32 v192, v122, v68, v192
	v_fma_f32 v192, v123, v70, v192
	v_fma_f32 v193, v121, v65, v73
	v_fma_f32 v193, v122, v67, v193
	v_fma_f32 v193, v123, v68, v193
	v_fma_f32 v193, v124, v70, v193
; __device__ __forceinline__ void lru_tile(const Params& P, int chunk, int head, int pass, char* smem_raw) {
;     ...
; #pragma unroll
;     for (int i = 0; i < 32; ++i) {
;       const float v = cb + uv[i] * w0 + uv[i + 1] * w1 + uv[i + 2] * w2 + uv[i + 3] * w3;
;       sm_uc[(q * 32 + i) * LDSS + ch] = f2bf(v);
;     }
;     ...
;   if (pass == 2 && tid < 128) {
;     const int d = tid >> 6;
;     float h = 0.f;
;     const float2* S = P.summ + (long)d * 264 * 512 + gch;
;     if (chunk < 256) {
;       const int b = chunk >> 6, j = chunk & 63;
;       if (d == 0) {
;         float2 s = S[(long)(256 + 2 * b) * 512]; h = s.x * h + s.y;
;         s = S[(long)(256 + 2 * b + 1) * 512]; h = s.x * h + s.y;
;         int i = 0;
;         for (; i + 8 <= j; i += 8) {
;           float2 sv[8];
; #pragma unroll
;           for (int u = 0; u < 8; ++u) sv[u] = S[(long)(b * 64 + i + u) * 512];
; #pragma unroll
;           for (int u = 0; u < 8; ++u) h = sv[u].x * h + sv[u].y;
;         }
;         for (; i < j; ++i) { s = S[(long)(b * 64 + i) * 512]; h = s.x * h + s.y; }
	v_cvt_pk_bf16_f32 v162, v162, v162
	v_cvt_pk_bf16_f32 v163, v163, v163
	v_cvt_pk_bf16_f32 v164, v164, v164
	v_cvt_pk_bf16_f32 v165, v165, v165
	v_cvt_pk_bf16_f32 v166, v166, v166
	v_cvt_pk_bf16_f32 v167, v167, v167
	v_cvt_pk_bf16_f32 v168, v168, v168
	v_cvt_pk_bf16_f32 v169, v169, v169
	v_cvt_pk_bf16_f32 v170, v170, v170
	v_cvt_pk_bf16_f32 v171, v171, v171
	v_cvt_pk_bf16_f32 v172, v172, v172
	v_cvt_pk_bf16_f32 v173, v173, v173
	v_cvt_pk_bf16_f32 v174, v174, v174
	v_cvt_pk_bf16_f32 v175, v175, v175
	v_cvt_pk_bf16_f32 v176, v176, v176
	v_cvt_pk_bf16_f32 v177, v177, v177
	v_cvt_pk_bf16_f32 v178, v178, v178
	v_cvt_pk_bf16_f32 v179, v179, v179
	v_cvt_pk_bf16_f32 v180, v180, v180
	v_cvt_pk_bf16_f32 v181, v181, v181
	v_cvt_pk_bf16_f32 v182, v182, v182
	v_cvt_pk_bf16_f32 v183, v183, v183
	v_cvt_pk_bf16_f32 v184, v184, v184
	v_cvt_pk_bf16_f32 v185, v185, v185
	v_cvt_pk_bf16_f32 v186, v186, v186
	v_cvt_pk_bf16_f32 v187, v187, v187
	v_cvt_pk_bf16_f32 v188, v188, v188
	v_cvt_pk_bf16_f32 v189, v189, v189
	v_cvt_pk_bf16_f32 v190, v190, v190
	v_cvt_pk_bf16_f32 v191, v191, v191
	v_cvt_pk_bf16_f32 v192, v192, v192
	v_cvt_pk_bf16_f32 v193, v193, v193
	ds_write_b16 v89, v162 offset:0
	ds_write_b16 v89, v163 offset:128
	ds_write_b16 v130, v164 offset:256
	ds_write_b16 v130, v165 offset:384
	ds_write_b16 v89, v166 offset:512
	ds_write_b16 v89, v167 offset:640
	ds_write_b16 v130, v168 offset:768
	ds_write_b16 v130, v169 offset:896
	ds_write_b16 v89, v170 offset:1024
	ds_write_b16 v89, v171 offset:1152
	ds_write_b16 v130, v172 offset:1280
	ds_write_b16 v130, v173 offset:1408
	ds_write_b16 v89, v174 offset:1536
	ds_write_b16 v89, v175 offset:1664
	ds_write_b16 v130, v176 offset:1792
	ds_write_b16 v130, v177 offset:1920
	ds_write_b16 v89, v178 offset:2048
	ds_write_b16 v89, v179 offset:2176
	ds_write_b16 v130, v180 offset:2304
	ds_write_b16 v130, v181 offset:2432
	ds_write_b16 v89, v182 offset:2560
	ds_write_b16 v89, v183 offset:2688
	ds_write_b16 v130, v184 offset:2816
	ds_write_b16 v130, v185 offset:2944
	ds_write_b16 v89, v186 offset:3072
	ds_write_b16 v89, v187 offset:3200
	ds_write_b16 v130, v188 offset:3328
	ds_write_b16 v130, v189 offset:3456
	ds_write_b16 v89, v190 offset:3584
	ds_write_b16 v89, v191 offset:3712
	ds_write_b16 v130, v192 offset:3840
	ds_write_b16 v130, v193 offset:3968
	v_lshlrev_b32_e32 v162, 16, v162
	v_lshlrev_b32_e32 v163, 16, v163
	v_lshlrev_b32_e32 v164, 16, v164
	v_lshlrev_b32_e32 v165, 16, v165
	v_lshlrev_b32_e32 v166, 16, v166
	v_lshlrev_b32_e32 v167, 16, v167
	v_lshlrev_b32_e32 v168, 16, v168
	v_lshlrev_b32_e32 v169, 16, v169
	v_lshlrev_b32_e32 v170, 16, v170
	v_lshlrev_b32_e32 v171, 16, v171
	v_lshlrev_b32_e32 v172, 16, v172
	v_lshlrev_b32_e32 v173, 16, v173
	v_lshlrev_b32_e32 v174, 16, v174
	v_lshlrev_b32_e32 v175, 16, v175
	v_lshlrev_b32_e32 v176, 16, v176
	v_lshlrev_b32_e32 v177, 16, v177
	v_lshlrev_b32_e32 v178, 16, v178
	v_lshlrev_b32_e32 v179, 16, v179
	v_lshlrev_b32_e32 v180, 16, v180
	v_lshlrev_b32_e32 v181, 16, v181
	v_lshlrev_b32_e32 v182, 16, v182
	v_lshlrev_b32_e32 v183, 16, v183
	v_lshlrev_b32_e32 v184, 16, v184
	v_lshlrev_b32_e32 v185, 16, v185
	v_lshlrev_b32_e32 v186, 16, v186
	v_lshlrev_b32_e32 v187, 16, v187
	v_lshlrev_b32_e32 v188, 16, v188
	v_lshlrev_b32_e32 v189, 16, v189
	v_lshlrev_b32_e32 v190, 16, v190
	v_lshlrev_b32_e32 v191, 16, v191
	v_lshlrev_b32_e32 v192, 16, v192
	v_lshlrev_b32_e32 v193, 16, v193
	s_waitcnt lgkmcnt(0)
	s_barrier
	v_mov_b32_e32 v148, 0
	v_mov_b32_e32 v149, 0
	s_cmp_lt_u32 s71, 256
	s_cbranch_scc0 .Lmy_lrub_lbctx
	s_lshl_b32 s0, s56, 3
	s_add_u32 s0, s0, 0x0
	s_add_u32 s4, s18, s0
	s_addc_u32 s5, s19, 0
	s_lshr_b32 s0, s71, 6
	s_lshl_b32 s1, s0, 1
	s_add_u32 s1, s1, 256
	s_add_u32 s60, s1, 0
	s_lshl_b32 s60, s60, 12
	s_add_u32 s60, s4, s60
	s_addc_u32 s61, s5, 0
	global_load_dwordx2 v[0:1], v250, s[60:61]
	s_add_u32 s60, s1, 1
	s_lshl_b32 s60, s60, 12
	s_add_u32 s60, s4, s60
	s_addc_u32 s61, s5, 0
	global_load_dwordx2 v[2:3], v250, s[60:61]
	s_lshl_b32 s0, s0, 6
	v_bfe_u32 v150, v152, 4, 2
	s_mov_b32 s1, s57
	v_lshl_add_u32 v136, v150, 16, v250
	s_lshl_b32 s60, s0, 12
	v_lshlrev_b32_e32 v150, 4, v150
	v_sub_u32_e32 v150, s1, v150
	s_add_u32 s60, s4, s60
	s_addc_u32 s61, s5, 0
	global_load_dwordx2 v[4:5], v136, s[60:61]
	s_add_u32 s60, s60, 0x1000
	s_addc_u32 s61, s61, 0
	global_load_dwordx2 v[6:7], v136, s[60:61]
	s_add_u32 s60, s60, 0x1000
	s_addc_u32 s61, s61, 0
	global_load_dwordx2 v[8:9], v136, s[60:61]
	s_add_u32 s60, s60, 0x1000
	s_addc_u32 s61, s61, 0
	global_load_dwordx2 v[10:11], v136, s[60:61]
	s_add_u32 s60, s60, 0x1000
	s_addc_u32 s61, s61, 0
	global_load_dwordx2 v[12:13], v136, s[60:61]
	s_add_u32 s60, s60, 0x1000
	s_addc_u32 s61, s61, 0
	global_load_dwordx2 v[14:15], v136, s[60:61]
	s_add_u32 s60, s60, 0x1000
	s_addc_u32 s61, s61, 0
	global_load_dwordx2 v[16:17], v136, s[60:61]
	s_add_u32 s60, s60, 0x1000
	s_addc_u32 s61, s61, 0
	global_load_dwordx2 v[18:19], v136, s[60:61]
	s_add_u32 s60, s60, 0x1000
	s_addc_u32 s61, s61, 0
	global_load_dwordx2 v[20:21], v136, s[60:61]
	s_add_u32 s60, s60, 0x1000
	s_addc_u32 s61, s61, 0
	global_load_dwordx2 v[22:23], v136, s[60:61]
	s_add_u32 s60, s60, 0x1000
	s_addc_u32 s61, s61, 0
	global_load_dwordx2 v[24:25], v136, s[60:61]
	s_add_u32 s60, s60, 0x1000
	s_addc_u32 s61, s61, 0
	global_load_dwordx2 v[26:27], v136, s[60:61]
	s_add_u32 s60, s60, 0x1000
	s_addc_u32 s61, s61, 0
	global_load_dwordx2 v[28:29], v136, s[60:61]
	s_add_u32 s60, s60, 0x1000
	s_addc_u32 s61, s61, 0
	global_load_dwordx2 v[30:31], v136, s[60:61]
	s_add_u32 s60, s60, 0x1000
	s_addc_u32 s61, s61, 0
	global_load_dwordx2 v[32:33], v136, s[60:61]
	s_add_u32 s60, s60, 0x1000
; __device__ __forceinline__ void lru_tile(const Params& P, int chunk, int head, int pass, char* smem_raw) {
;     ...
;     const float2* S = P.summ + (long)d * 264 * 512 + gch;
;     if (chunk < 256) {
;       const int b = chunk >> 6, j = chunk & 63;
;       if (d == 0) {
;         float2 s = S[(long)(256 + 2 * b) * 512]; h = s.x * h + s.y;
;         s = S[(long)(256 + 2 * b + 1) * 512]; h = s.x * h + s.y;
;         int i = 0;
;         for (; i + 8 <= j; i += 8) {
;           float2 sv[8];
; #pragma unroll
;           for (int u = 0; u < 8; ++u) sv[u] = S[(long)(b * 64 + i + u) * 512];
; #pragma unroll
;           for (int u = 0; u < 8; ++u) h = sv[u].x * h + sv[u].y;
;         }
;         for (; i < j; ++i) { s = S[(long)(b * 64 + i) * 512]; h = s.x * h + s.y; }
;       } else {
;         float2 s = S[(long)(256 + 2 * b + 1) * 512]; h = s.x * h + s.y;
;         s = S[(long)(256 + 2 * b) * 512]; h = s.x * h + s.y;
;         int i = 63;
;         for (; i - 8 >= j; i -= 8) {
;           float2 sv[8];
; #pragma unroll
;           for (int u = 0; u < 8; ++u) sv[u] = S[(long)(b * 64 + i - u) * 512];
; #pragma unroll
;           for (int u = 0; u < 8; ++u) h = sv[u].x * h + sv[u].y;
;         }
;         for (; i > j; --i) { s = S[(long)(b * 64 + i) * 512]; h = s.x * h + s.y; }
	s_addc_u32 s61, s61, 0
	global_load_dwordx2 v[34:35], v136, s[60:61]
	s_lshl_b32 s0, s56, 3
	s_add_u32 s0, s0, 0x108000
	s_add_u32 s4, s18, s0
	s_addc_u32 s5, s19, 0
	s_lshr_b32 s0, s71, 6
	s_lshl_b32 s1, s0, 1
	s_add_u32 s1, s1, 256
	s_add_u32 s60, s1, 1
	s_lshl_b32 s60, s60, 12
	s_add_u32 s60, s4, s60
	s_addc_u32 s61, s5, 0
	global_load_dwordx2 v[90:91], v250, s[60:61]
	s_add_u32 s60, s1, 0
	s_lshl_b32 s60, s60, 12
	s_add_u32 s60, s4, s60
	s_addc_u32 s61, s5, 0
	global_load_dwordx2 v[92:93], v250, s[60:61]
	s_lshl_b32 s0, s0, 6
	v_bfe_u32 v202, v152, 4, 2
	s_sub_u32 s1, 63, s57
	v_sub_u32_e32 v151, 3, v202
	v_lshl_add_u32 v151, v151, 16, v250
	s_add_u32 s60, s0, 15
	s_lshl_b32 s60, s60, 12
	v_lshlrev_b32_e32 v202, 4, v202
	v_sub_u32_e32 v202, s1, v202
	s_add_u32 s60, s4, s60
	s_addc_u32 s61, s5, 0
	global_load_dwordx2 v[94:95], v151, s[60:61]
	s_sub_u32 s60, s60, 0x1000
	s_subb_u32 s61, s61, 0
	global_load_dwordx2 v[96:97], v151, s[60:61]
	s_sub_u32 s60, s60, 0x1000
	s_subb_u32 s61, s61, 0
	global_load_dwordx2 v[98:99], v151, s[60:61]
	s_sub_u32 s60, s60, 0x1000
	s_subb_u32 s61, s61, 0
	global_load_dwordx2 v[100:101], v151, s[60:61]
	s_sub_u32 s60, s60, 0x1000
	s_subb_u32 s61, s61, 0
	global_load_dwordx2 v[102:103], v151, s[60:61]
	s_sub_u32 s60, s60, 0x1000
	s_subb_u32 s61, s61, 0
	global_load_dwordx2 v[104:105], v151, s[60:61]
	s_sub_u32 s60, s60, 0x1000
	s_subb_u32 s61, s61, 0
	global_load_dwordx2 v[106:107], v151, s[60:61]
	s_sub_u32 s60, s60, 0x1000
	s_subb_u32 s61, s61, 0
	global_load_dwordx2 v[108:109], v151, s[60:61]
	s_sub_u32 s60, s60, 0x1000
	s_subb_u32 s61, s61, 0
	global_load_dwordx2 v[110:111], v151, s[60:61]
	s_sub_u32 s60, s60, 0x1000
	s_subb_u32 s61, s61, 0
	global_load_dwordx2 v[112:113], v151, s[60:61]
	s_sub_u32 s60, s60, 0x1000
	s_subb_u32 s61, s61, 0
	global_load_dwordx2 v[114:115], v151, s[60:61]
	s_sub_u32 s60, s60, 0x1000
	s_subb_u32 s61, s61, 0
	global_load_dwordx2 v[116:117], v151, s[60:61]
	s_sub_u32 s60, s60, 0x1000
	s_subb_u32 s61, s61, 0
	global_load_dwordx2 v[118:119], v151, s[60:61]
	s_sub_u32 s60, s60, 0x1000
	s_subb_u32 s61, s61, 0
	global_load_dwordx2 v[120:121], v151, s[60:61]
	s_sub_u32 s60, s60, 0x1000
	s_subb_u32 s61, s61, 0
	global_load_dwordx2 v[122:123], v151, s[60:61]
	s_sub_u32 s60, s60, 0x1000
	s_subb_u32 s61, s61, 0
	global_load_dwordx2 v[124:125], v151, s[60:61]
	s_waitcnt vmcnt(34)
	v_fma_f32 v148, v0, v148, v1
	v_fma_f32 v148, v2, v148, v3
	v_mov_b32_e32 v253, 1.0
	v_mov_b32_e32 v254, 0
	s_waitcnt vmcnt(18)
	v_cmp_lt_i32_e32 vcc, 0, v150
	s_nop 1
	v_cndmask_b32_e32 v4, 1.0, v4, vcc
	v_cndmask_b32_e32 v5, 0, v5, vcc
	v_fma_f32 v254, v4, v254, v5
	v_mul_f32_e32 v253, v253, v4
	v_cmp_lt_i32_e32 vcc, 1, v150
	s_nop 1
	v_cndmask_b32_e32 v6, 1.0, v6, vcc
	v_cndmask_b32_e32 v7, 0, v7, vcc
	v_fma_f32 v254, v6, v254, v7
	v_mul_f32_e32 v253, v253, v6
	v_cmp_lt_i32_e32 vcc, 2, v150
	s_nop 1
	v_cndmask_b32_e32 v8, 1.0, v8, vcc
	v_cndmask_b32_e32 v9, 0, v9, vcc
	v_fma_f32 v254, v8, v254, v9
	v_mul_f32_e32 v253, v253, v8
	v_cmp_lt_i32_e32 vcc, 3, v150
	s_nop 1
	v_cndmask_b32_e32 v10, 1.0, v10, vcc
	v_cndmask_b32_e32 v11, 0, v11, vcc
	v_fma_f32 v254, v10, v254, v11
	v_mul_f32_e32 v253, v253, v10
	v_cmp_lt_i32_e32 vcc, 4, v150
	s_nop 1
	v_cndmask_b32_e32 v12, 1.0, v12, vcc
	v_cndmask_b32_e32 v13, 0, v13, vcc
	v_fma_f32 v254, v12, v254, v13
	v_mul_f32_e32 v253, v253, v12
	v_cmp_lt_i32_e32 vcc, 5, v150
	s_nop 1
	v_cndmask_b32_e32 v14, 1.0, v14, vcc
	v_cndmask_b32_e32 v15, 0, v15, vcc
	v_fma_f32 v254, v14, v254, v15
	v_mul_f32_e32 v253, v253, v14
	v_cmp_lt_i32_e32 vcc, 6, v150
	s_nop 1
	v_cndmask_b32_e32 v16, 1.0, v16, vcc
	v_cndmask_b32_e32 v17, 0, v17, vcc
	v_fma_f32 v254, v16, v254, v17
	v_mul_f32_e32 v253, v253, v16
	v_cmp_lt_i32_e32 vcc, 7, v150
	s_nop 1
	v_cndmask_b32_e32 v18, 1.0, v18, vcc
	v_cndmask_b32_e32 v19, 0, v19, vcc
	v_fma_f32 v254, v18, v254, v19
	v_mul_f32_e32 v253, v253, v18
	v_cmp_lt_i32_e32 vcc, 8, v150
	s_nop 1
	v_cndmask_b32_e32 v20, 1.0, v20, vcc
	v_cndmask_b32_e32 v21, 0, v21, vcc
	v_fma_f32 v254, v20, v254, v21
	v_mul_f32_e32 v253, v253, v20
	v_cmp_lt_i32_e32 vcc, 9, v150
	s_nop 1
	v_cndmask_b32_e32 v22, 1.0, v22, vcc
	v_cndmask_b32_e32 v23, 0, v23, vcc
	v_fma_f32 v254, v22, v254, v23
	v_mul_f32_e32 v253, v253, v22
	v_cmp_lt_i32_e32 vcc, 10, v150
	s_nop 1
	v_cndmask_b32_e32 v24, 1.0, v24, vcc
	v_cndmask_b32_e32 v25, 0, v25, vcc
	v_fma_f32 v254, v24, v254, v25
	v_mul_f32_e32 v253, v253, v24
	v_cmp_lt_i32_e32 vcc, 11, v150
	s_nop 1
	v_cndmask_b32_e32 v26, 1.0, v26, vcc
	v_cndmask_b32_e32 v27, 0, v27, vcc
	v_fma_f32 v254, v26, v254, v27
	v_mul_f32_e32 v253, v253, v26
	v_cmp_lt_i32_e32 vcc, 12, v150
	s_nop 1
	v_cndmask_b32_e32 v28, 1.0, v28, vcc
	v_cndmask_b32_e32 v29, 0, v29, vcc
	v_fma_f32 v254, v28, v254, v29
	v_mul_f32_e32 v253, v253, v28
	v_cmp_lt_i32_e32 vcc, 13, v150
	s_nop 1
	v_cndmask_b32_e32 v30, 1.0, v30, vcc
	v_cndmask_b32_e32 v31, 0, v31, vcc
	v_fma_f32 v254, v30, v254, v31
	v_mul_f32_e32 v253, v253, v30
	v_cmp_lt_i32_e32 vcc, 14, v150
	s_nop 1
	v_cndmask_b32_e32 v32, 1.0, v32, vcc
	v_cndmask_b32_e32 v33, 0, v33, vcc
	v_fma_f32 v254, v32, v254, v33
	v_mul_f32_e32 v253, v253, v32
	v_cmp_lt_i32_e32 vcc, 15, v150
	s_nop 1
	v_cndmask_b32_e32 v34, 1.0, v34, vcc
	v_cndmask_b32_e32 v35, 0, v35, vcc
	v_fma_f32 v254, v34, v254, v35
	v_mul_f32_e32 v253, v253, v34
	v_mov_b32_e32 v138, v253
	v_mov_b32_e32 v139, v253
	s_nop 1
	v_permlane16_swap_b32_e32 v138, v139
	v_mov_b32_e32 v140, v138
	v_mov_b32_e32 v141, v139
	s_nop 1
	v_permlane32_swap_b32_e32 v138, v140
	v_permlane32_swap_b32_e32 v139, v141
	v_mov_b32_e32 v198, v254
	v_mov_b32_e32 v199, v254
	s_nop 1
	v_permlane16_swap_b32_e32 v198, v199
	v_mov_b32_e32 v200, v198
	v_mov_b32_e32 v201, v199
	s_nop 1
	v_permlane32_swap_b32_e32 v198, v200
	v_permlane32_swap_b32_e32 v199, v201
	v_fma_f32 v148, v138, v148, v198
	v_fma_f32 v148, v139, v148, v199
	v_fma_f32 v148, v140, v148, v200
	v_fma_f32 v148, v141, v148, v201
	s_waitcnt vmcnt(16)
; __device__ __forceinline__ void lru_tile(const Params& P, int chunk, int head, int pass, char* smem_raw) {
;     ...
;       } else {
;         float2 s = S[(long)(256 + 2 * b + 1) * 512]; h = s.x * h + s.y;
;         s = S[(long)(256 + 2 * b) * 512]; h = s.x * h + s.y;
;         int i = 63;
;         for (; i - 8 >= j; i -= 8) {
;           float2 sv[8];
; #pragma unroll
;           for (int u = 0; u < 8; ++u) sv[u] = S[(long)(b * 64 + i - u) * 512];
; #pragma unroll
;           for (int u = 0; u < 8; ++u) h = sv[u].x * h + sv[u].y;
;         }
;         for (; i > j; --i) { s = S[(long)(b * 64 + i) * 512]; h = s.x * h + s.y; }
;       }
	v_fma_f32 v149, v90, v149, v91
	v_fma_f32 v149, v92, v149, v93
	v_mov_b32_e32 v253, 1.0
	v_mov_b32_e32 v254, 0
	s_waitcnt vmcnt(0)
	v_cmp_lt_i32_e32 vcc, 0, v202
	s_nop 1
	v_cndmask_b32_e32 v94, 1.0, v94, vcc
	v_cndmask_b32_e32 v95, 0, v95, vcc
	v_fma_f32 v254, v94, v254, v95
	v_mul_f32_e32 v253, v253, v94
	v_cmp_lt_i32_e32 vcc, 1, v202
	s_nop 1
	v_cndmask_b32_e32 v96, 1.0, v96, vcc
	v_cndmask_b32_e32 v97, 0, v97, vcc
	v_fma_f32 v254, v96, v254, v97
	v_mul_f32_e32 v253, v253, v96
	v_cmp_lt_i32_e32 vcc, 2, v202
	s_nop 1
	v_cndmask_b32_e32 v98, 1.0, v98, vcc
	v_cndmask_b32_e32 v99, 0, v99, vcc
	v_fma_f32 v254, v98, v254, v99
	v_mul_f32_e32 v253, v253, v98
	v_cmp_lt_i32_e32 vcc, 3, v202
	s_nop 1
	v_cndmask_b32_e32 v100, 1.0, v100, vcc
	v_cndmask_b32_e32 v101, 0, v101, vcc
	v_fma_f32 v254, v100, v254, v101
	v_mul_f32_e32 v253, v253, v100
	v_cmp_lt_i32_e32 vcc, 4, v202
	s_nop 1
	v_cndmask_b32_e32 v102, 1.0, v102, vcc
	v_cndmask_b32_e32 v103, 0, v103, vcc
	v_fma_f32 v254, v102, v254, v103
	v_mul_f32_e32 v253, v253, v102
	v_cmp_lt_i32_e32 vcc, 5, v202
	s_nop 1
	v_cndmask_b32_e32 v104, 1.0, v104, vcc
	v_cndmask_b32_e32 v105, 0, v105, vcc
	v_fma_f32 v254, v104, v254, v105
	v_mul_f32_e32 v253, v253, v104
	v_cmp_lt_i32_e32 vcc, 6, v202
	s_nop 1
	v_cndmask_b32_e32 v106, 1.0, v106, vcc
	v_cndmask_b32_e32 v107, 0, v107, vcc
	v_fma_f32 v254, v106, v254, v107
	v_mul_f32_e32 v253, v253, v106
	v_cmp_lt_i32_e32 vcc, 7, v202
	s_nop 1
	v_cndmask_b32_e32 v108, 1.0, v108, vcc
	v_cndmask_b32_e32 v109, 0, v109, vcc
	v_fma_f32 v254, v108, v254, v109
	v_mul_f32_e32 v253, v253, v108
	v_cmp_lt_i32_e32 vcc, 8, v202
	s_nop 1
	v_cndmask_b32_e32 v110, 1.0, v110, vcc
	v_cndmask_b32_e32 v111, 0, v111, vcc
	v_fma_f32 v254, v110, v254, v111
	v_mul_f32_e32 v253, v253, v110
	v_cmp_lt_i32_e32 vcc, 9, v202
	s_nop 1
	v_cndmask_b32_e32 v112, 1.0, v112, vcc
	v_cndmask_b32_e32 v113, 0, v113, vcc
	v_fma_f32 v254, v112, v254, v113
	v_mul_f32_e32 v253, v253, v112
	v_cmp_lt_i32_e32 vcc, 10, v202
	s_nop 1
	v_cndmask_b32_e32 v114, 1.0, v114, vcc
	v_cndmask_b32_e32 v115, 0, v115, vcc
	v_fma_f32 v254, v114, v254, v115
	v_mul_f32_e32 v253, v253, v114
	v_cmp_lt_i32_e32 vcc, 11, v202
	s_nop 1
	v_cndmask_b32_e32 v116, 1.0, v116, vcc
	v_cndmask_b32_e32 v117, 0, v117, vcc
	v_fma_f32 v254, v116, v254, v117
	v_mul_f32_e32 v253, v253, v116
	v_cmp_lt_i32_e32 vcc, 12, v202
	s_nop 1
	v_cndmask_b32_e32 v118, 1.0, v118, vcc
	v_cndmask_b32_e32 v119, 0, v119, vcc
	v_fma_f32 v254, v118, v254, v119
	v_mul_f32_e32 v253, v253, v118
	v_cmp_lt_i32_e32 vcc, 13, v202
	s_nop 1
	v_cndmask_b32_e32 v120, 1.0, v120, vcc
	v_cndmask_b32_e32 v121, 0, v121, vcc
	v_fma_f32 v254, v120, v254, v121
	v_mul_f32_e32 v253, v253, v120
	v_cmp_lt_i32_e32 vcc, 14, v202
	s_nop 1
	v_cndmask_b32_e32 v122, 1.0, v122, vcc
	v_cndmask_b32_e32 v123, 0, v123, vcc
	v_fma_f32 v254, v122, v254, v123
	v_mul_f32_e32 v253, v253, v122
	v_cmp_lt_i32_e32 vcc, 15, v202
	s_nop 1
	v_cndmask_b32_e32 v124, 1.0, v124, vcc
	v_cndmask_b32_e32 v125, 0, v125, vcc
	v_fma_f32 v254, v124, v254, v125
	v_mul_f32_e32 v253, v253, v124
	v_mov_b32_e32 v138, v253
	v_mov_b32_e32 v139, v253
	s_nop 1
	v_permlane16_swap_b32_e32 v138, v139
	v_mov_b32_e32 v140, v138
	v_mov_b32_e32 v141, v139
	s_nop 1
	v_permlane32_swap_b32_e32 v138, v140
	v_permlane32_swap_b32_e32 v139, v141
	v_mov_b32_e32 v198, v254
	v_mov_b32_e32 v199, v254
	s_nop 1
	v_permlane16_swap_b32_e32 v198, v199
	v_mov_b32_e32 v200, v198
	v_mov_b32_e32 v201, v199
	s_nop 1
	v_permlane32_swap_b32_e32 v198, v200
	v_permlane32_swap_b32_e32 v199, v201
	v_fma_f32 v149, v138, v149, v198
	v_fma_f32 v149, v139, v149, v199
	v_fma_f32 v149, v140, v149, v200
	v_fma_f32 v149, v141, v149, v201
	s_branch .Lmy_lrub_lbdone
